# v12 + stick-breaking loop: all 8 K fragments read up front with counted waits, first-half V^T reads hoisted into the MFMA-to-VALU gap, second-half V^T reads into separate registers so the 8 PV MFMAs r
# speedup vs baseline: 1.0008x; 1.0008x over previous
.LBB0_388:
	s_and_b32 s46, s69, 8
	s_xor_b32 s66, s46, 8
	s_add_i32 s67, 0, 0x10000
	s_lshl_b32 s66, s66, 2
	s_add_i32 s66, s67, s66
	v_mov_b32_e32 v1, s66
	s_waitcnt vmcnt(4)
	s_waitcnt lgkmcnt(0)
	s_barrier
	ds_read_b128 v[68:71], v1
	ds_read_b128 v[72:75], v1 offset:16
	s_mov_b64 s[90:91], -1
	s_waitcnt lgkmcnt(0)
	v_and_b32_e32 v1, v68, v69
	v_and_b32_e32 v2, v70, v71
	v_and_b32_e32 v68, v72, v73
	v_and_b32_e32 v69, v74, v75
	v_and_b32_e32 v1, v1, v2
	v_and_b32_e32 v68, v68, v69
	v_and_b32_e32 v1, v1, v68
	v_and_b32_e32 v1, 1, v1
	v_cmp_eq_u32_e32 vcc, 1, v1
	s_nop 1
	s_and_b64 vcc, exec, vcc
	s_cbranch_vccnz .LBB0_387
	s_max_i32 s66, s1, 3
	s_lshl_b32 s66, s66, 5
	s_addk_i32 s66, 0xffa0
	s_and_b32 s90, s4, 0xc000
	s_ashr_i32 s67, s66, 31
	s_lshl_b64 s[66:67], s[66:67], 12
	s_add_i32 s90, s94, s90
	v_lshl_add_u64 v[68:69], v[174:175], 0, s[66:67]
	s_mov_b32 m0, s90
	s_nop 0
	global_load_lds_dwordx4 v[68:69], off
	v_lshl_add_u64 v[68:69], v[176:177], 0, s[66:67]
	s_add_i32 m0, s90, 0x2000
	s_cmp_gt_i32 s1, s79
	global_load_lds_dwordx4 v[68:69], off
	s_cselect_b64 s[66:67], -1, 0
	s_or_b64 s[66:67], s[66:67], s[86:87]
	s_and_b64 vcc, exec, s[66:67]
	s_cbranch_vccnz .LBB0_394
	s_add_i32 s66, s4, 0xffff4000
	s_and_b32 s66, s66, 0xc000
	s_add_i32 s90, s66, 0
	v_add_u32_e32 v1, s90, v181
	v_add_u32_e32 v2, v1, v183
	ds_read_b128 v[68:71], v2
	v_add_u32_e32 v2, v1, v184
	ds_read_b128 v[84:87], v2
	v_add_u32_e32 v2, v1, v185
	ds_read_b128 v[88:91], v2
	v_add_u32_e32 v2, v1, v186
	ds_read_b128 v[228:231], v2
	v_add_u32_e32 v2, v1, v187
	ds_read_b128 v[232:235], v2
	v_add_u32_e32 v2, v1, v188
	ds_read_b128 v[236:239], v2
	v_add_u32_e32 v2, v1, v189
	ds_read_b128 v[240:243], v2
	v_add_u32_e32 v1, v1, v190
	ds_read_b128 v[244:247], v1
	s_cmp_eq_u32 s76, 0
	s_cselect_b64 s[86:87], -1, 0
	s_cmp_lg_u32 s76, 0
	s_waitcnt lgkmcnt(7)
	v_mfma_f32_32x32x16_bf16 v[68:83], v[68:71], v[132:135], 0
	s_waitcnt lgkmcnt(6)
	v_mfma_f32_32x32x16_bf16 v[68:83], v[84:87], v[136:139], v[68:83]
	s_waitcnt lgkmcnt(5)
	v_mfma_f32_32x32x16_bf16 v[68:83], v[88:91], v[140:143], v[68:83]
	s_waitcnt lgkmcnt(4)
	v_mfma_f32_32x32x16_bf16 v[68:83], v[228:231], v[144:147], v[68:83]
	s_waitcnt lgkmcnt(3)
	v_mfma_f32_32x32x16_bf16 v[68:83], v[232:235], v[148:151], v[68:83]
	s_waitcnt lgkmcnt(2)
	v_mfma_f32_32x32x16_bf16 v[68:83], v[236:239], v[152:155], v[68:83]
	s_waitcnt lgkmcnt(1)
	v_mfma_f32_32x32x16_bf16 v[68:83], v[240:243], v[156:159], v[68:83]
	s_waitcnt lgkmcnt(0)
	v_mfma_f32_32x32x16_bf16 v[68:83], v[244:247], v[160:163], v[68:83]
	v_add_u32_e32 v248, s90, v180
	v_add_u32_e32 v249, s90, v167
	v_add_u32_e32 v222, s90, v191
	v_add_u32_e32 v223, s90, v192
	v_add_u32_e32 v224, s90, v193
	v_add_u32_e32 v225, s90, v194
	v_add_u32_e32 v226, s90, v195
	v_add_u32_e32 v227, s90, v196
	ds_read_b64_tr_b16 v[228:229], v248 offset:8192
	ds_read_b64_tr_b16 v[230:231], v249 offset:9216
	ds_read_b64_tr_b16 v[232:233], v222 offset:8192
	ds_read_b64_tr_b16 v[234:235], v223 offset:8192
	ds_read_b64_tr_b16 v[236:237], v224 offset:8192
	ds_read_b64_tr_b16 v[238:239], v225 offset:8192
	ds_read_b64_tr_b16 v[240:241], v226 offset:8192
	ds_read_b64_tr_b16 v[242:243], v227 offset:8192
	v_exp_f32_e64 v1, -|v68|
	v_exp_f32_e64 v84, -|v69|
	v_exp_f32_e64 v88, -|v71|
	v_exp_f32_e64 v86, -|v70|
	v_exp_f32_e64 v90, -|v72|
	v_exp_f32_e64 v92, -|v73|
	v_add_f32_e32 v1, 1.0, v1
	v_add_f32_e32 v84, 1.0, v84
	v_add_f32_e32 v88, 1.0, v88
	v_log_f32_e32 v1, v1
	v_exp_f32_e64 v94, -|v74|
	v_add_f32_e32 v86, 1.0, v86
	v_add_f32_e32 v90, 1.0, v90
	v_log_f32_e32 v84, v84
	v_log_f32_e32 v88, v88
	v_log_f32_e32 v86, v86
	v_log_f32_e32 v90, v90
	v_max_f32_e32 v2, 0, v68
	v_add_f32_e32 v92, 1.0, v92
	v_max_f32_e32 v85, 0, v69
	v_max_f32_e32 v89, 0, v71
	v_log_f32_e32 v92, v92
	v_add_f32_e32 v1, v2, v1
	v_max_f32_e32 v87, 0, v70
	v_max_f32_e32 v91, 0, v72
	v_add_f32_e32 v94, 1.0, v94
	v_add_f32_e32 v2, v85, v84
	v_add_f32_e32 v85, v89, v88
	v_cndmask_b32_e64 v89, 0, -v1, s[10:11]
	v_log_f32_e32 v94, v94
	v_add_f32_e32 v84, v87, v86
	v_add_f32_e32 v86, v91, v90
	v_cndmask_b32_e64 v90, 0, -v2, s[12:13]
	v_cndmask_b32_e64 v98, -v1, v89, s[86:87]
	v_max_f32_e32 v93, 0, v73
	v_cndmask_b32_e64 v91, 0, -v84, s[14:15]
	v_cndmask_b32_e64 v90, -v2, v90, s[86:87]
	v_add_f32_e32 v1, 0, v98
	v_exp_f32_e64 v96, -|v75|
	v_add_f32_e32 v87, v93, v92
	v_cndmask_b32_e64 v92, 0, -v85, s[16:17]
	v_cndmask_b32_e64 v91, -v84, v91, s[86:87]
	v_add_f32_e32 v1, v90, v1
	v_max_f32_e32 v95, 0, v74
	v_cndmask_b32_e64 v93, 0, -v86, s[18:19]
	v_cndmask_b32_e64 v92, -v85, v92, s[86:87]
	v_add_f32_e32 v1, v91, v1
	v_add_f32_e32 v88, v95, v94
	v_cndmask_b32_e64 v94, 0, -v87, s[20:21]
	v_cndmask_b32_e64 v93, -v86, v93, s[86:87]
	v_add_f32_e32 v1, v92, v1
	v_cndmask_b32_e64 v87, -v87, v94, s[86:87]
	v_add_f32_e32 v1, v93, v1
	v_add_f32_e32 v96, 1.0, v96
	v_add_f32_e32 v86, v87, v1
	v_exp_f32_e64 v1, -|v76|
	v_log_f32_e32 v96, v96
	v_max_f32_e32 v97, 0, v75
	v_add_f32_e32 v1, 1.0, v1
	v_add_f32_e32 v2, v97, v96
	v_log_f32_e32 v1, v1
	v_cndmask_b32_e64 v84, 0, -v2, s[24:25]
	v_cndmask_b32_e64 v94, -v2, v84, s[86:87]
	v_exp_f32_e64 v84, -|v77|
	v_max_f32_e32 v2, 0, v76
	v_add_f32_e32 v1, v2, v1
	v_cndmask_b32_e64 v2, 0, -v1, s[26:27]
	v_cndmask_b32_e64 v89, -v1, v2, s[86:87]
	v_add_f32_e32 v1, 1.0, v84
	v_log_f32_e32 v1, v1
	v_max_f32_e32 v84, 0, v77
	v_add_f32_e32 v2, 0, v89
	v_add_f32_e32 v1, v84, v1
	v_exp_f32_e64 v84, -|v78|
	v_cndmask_b32_e64 v85, 0, -v1, s[28:29]
	v_cndmask_b32_e64 v96, -v1, v85, s[86:87]
	v_add_f32_e32 v1, v96, v2
	v_add_f32_e32 v2, 1.0, v84
	v_log_f32_e32 v2, v2
	v_exp_f32_e64 v85, -|v79|
	v_max_f32_e32 v84, 0, v78
	v_add_f32_e32 v2, v84, v2
	v_cndmask_b32_e64 v84, 0, -v2, s[30:31]
	v_cndmask_b32_e64 v97, -v2, v84, s[86:87]
	v_add_f32_e32 v2, 1.0, v85
	v_log_f32_e32 v2, v2
	v_max_f32_e32 v84, 0, v79
	v_add_f32_e32 v1, v97, v1
	v_add_f32_e32 v2, v84, v2
	v_exp_f32_e64 v84, -|v80|
	v_cndmask_b32_e64 v85, 0, -v2, s[34:35]
	v_cndmask_b32_e64 v99, -v2, v85, s[86:87]
	v_exp_f32_e64 v85, -|v81|
	v_add_f32_e32 v2, 1.0, v84
	v_log_f32_e32 v2, v2
	v_max_f32_e32 v84, 0, v80
	v_add_f32_e32 v1, v99, v1
	v_add_f32_e32 v2, v84, v2
	v_cndmask_b32_e64 v84, 0, -v2, s[36:37]
	v_cndmask_b32_e64 v100, -v2, v84, s[86:87]
	v_add_f32_e32 v2, 1.0, v85
	v_log_f32_e32 v2, v2
	v_max_f32_e32 v84, 0, v81
	v_add_f32_e32 v1, v100, v1
	v_add_f32_e32 v2, v84, v2
	v_exp_f32_e64 v84, -|v82|
	v_cndmask_b32_e64 v85, 0, -v2, s[38:39]
	v_cndmask_b32_e64 v101, -v2, v85, s[86:87]
	v_exp_f32_e64 v85, -|v83|
	v_add_f32_e32 v2, 1.0, v84
	v_log_f32_e32 v2, v2
	v_max_f32_e32 v84, 0, v82
	v_add_f32_e32 v1, v101, v1
	v_add_f32_e32 v2, v84, v2
	v_cndmask_b32_e64 v84, 0, -v2, s[40:41]
	v_cndmask_b32_e64 v102, -v2, v84, s[86:87]
	v_add_f32_e32 v2, 1.0, v85
	v_log_f32_e32 v2, v2
	v_max_f32_e32 v84, 0, v83
	v_add_f32_e32 v1, v102, v1
	v_add_f32_e32 v2, v84, v2
	v_cndmask_b32_e64 v84, 0, -v2, s[42:43]
	v_cndmask_b32_e64 v2, -v2, v84, s[86:87]
	v_add_f32_e32 v84, v2, v1
	v_mov_b32_e32 v1, v84
	v_mov_b32_e32 v85, v84
	s_nop 1
	v_permlane32_swap_b32_e32 v1, v85
	v_cndmask_b32_e64 v85, v1, v85, s[2:3]
	v_add_f32_e32 v1, v173, v85
	v_cndmask_b32_e64 v103, v173, v1, s[6:7]
	v_add_f32_e32 v105, v1, v84
	v_add_f32_e32 v1, v83, v2
	v_add_f32_e32 v83, v103, v2
	v_add_f32_e32 v2, v82, v102
	v_add_f32_e32 v82, v102, v83
	v_add_f32_e32 v81, v81, v101
	v_add_f32_e32 v81, v81, v82
	v_add_f32_e32 v82, v101, v82
	v_add_f32_e32 v80, v80, v100
	v_add_f32_e32 v80, v80, v82
	v_add_f32_e32 v82, v100, v82
	v_add_f32_e32 v79, v79, v99
	v_add_f32_e32 v79, v79, v82
	v_add_f32_e32 v82, v99, v82
	v_add_f32_e32 v78, v78, v97
	v_cndmask_b32_e64 v95, 0, -v88, s[22:23]
	v_add_f32_e32 v78, v78, v82
	v_add_f32_e32 v82, v97, v82
	v_add_f32_e32 v77, v77, v96
	v_add_f32_e32 v77, v77, v82
	v_add_f32_e32 v82, v96, v82
	v_add_f32_e32 v76, v76, v89
	v_cndmask_b32_e64 v88, -v88, v95, s[86:87]
	v_add_f32_e32 v76, v76, v82
	v_add_f32_e32 v82, v88, v86
	v_add_f32_e32 v82, v94, v82
	v_mov_b32_e32 v86, v82
	v_mov_b32_e32 v89, v82
	s_nop 1
	v_permlane32_swap_b32_e32 v86, v89
	v_add_f32_e32 v104, v173, v84
	v_cndmask_b32_e64 v86, v86, v89, s[2:3]
	v_add_f32_e32 v2, v83, v2
	v_add_f32_e32 v83, v104, v85
	v_add_f32_e32 v89, v105, v86
	v_add_f32_e32 v75, v75, v94
	v_cndmask_b32_e64 v89, v83, v89, s[6:7]
	v_add_f32_e32 v75, v75, v89
	v_exp_f32_e32 v83, v75
	v_mov_b32_e32 v75, v94
	v_pk_add_f32 v[74:75], v[74:75], v[88:89]
	v_add_f32_e32 v73, v73, v87
	v_add_f32_e32 v74, v74, v75
	v_add_f32_e32 v75, v88, v75
	v_add_f32_e32 v73, v73, v75
	v_add_f32_e32 v75, v87, v75
	v_add_f32_e32 v72, v72, v93
	v_add_f32_e32 v72, v72, v75
	v_add_f32_e32 v75, v93, v75
	v_add_f32_e32 v71, v71, v92
	v_add_f32_e32 v71, v71, v75
	v_add_f32_e32 v75, v92, v75
	v_add_f32_e32 v70, v70, v91
	v_add_f32_e32 v70, v70, v75
	v_add_f32_e32 v75, v91, v75
	v_add_f32_e32 v69, v69, v90
	v_add_f32_e32 v69, v69, v75
	v_add_f32_e32 v75, v90, v75
	v_add_f32_e32 v68, v68, v98
	v_add_f32_e32 v1, v103, v1
	v_add_f32_e32 v68, v68, v75
	v_exp_f32_e32 v1, v1
	v_exp_f32_e32 v2, v2
	v_exp_f32_e32 v81, v81
	v_exp_f32_e32 v80, v80
	v_exp_f32_e32 v79, v79
	v_exp_f32_e32 v78, v78
	v_exp_f32_e32 v77, v77
	v_exp_f32_e32 v76, v76
	v_exp_f32_e32 v74, v74
	v_exp_f32_e32 v73, v73
	v_exp_f32_e32 v72, v72
	v_exp_f32_e32 v71, v71
	v_exp_f32_e32 v70, v70
	v_exp_f32_e32 v69, v69
	v_exp_f32_e32 v68, v68
	s_cbranch_scc1 .LBB0_392
	s_or_b64 vcc, s[12:13], s[10:11]
	v_cndmask_b32_e32 v68, 0, v68, vcc
	s_or_b64 vcc, s[16:17], s[14:15]
	v_cndmask_b32_e32 v70, 0, v70, vcc
	s_or_b64 vcc, s[20:21], s[18:19]
	v_cndmask_b32_e32 v72, 0, v72, vcc
	s_or_b64 vcc, s[24:25], s[22:23]
	v_cndmask_b32_e32 v74, 0, v74, vcc
	s_or_b64 vcc, s[28:29], s[26:27]
	v_cndmask_b32_e32 v76, 0, v76, vcc
	s_or_b64 vcc, s[34:35], s[30:31]
	v_cndmask_b32_e32 v78, 0, v78, vcc
	s_or_b64 vcc, s[38:39], s[36:37]
	v_cndmask_b32_e32 v80, 0, v80, vcc
	s_or_b64 vcc, s[42:43], s[40:41]
	v_cndmask_b32_e64 v69, 0, v69, s[12:13]
	v_cndmask_b32_e64 v71, 0, v71, s[16:17]
	v_cndmask_b32_e64 v73, 0, v73, s[20:21]
	v_cndmask_b32_e64 v83, 0, v83, s[24:25]
	v_cndmask_b32_e64 v77, 0, v77, s[28:29]
	v_cndmask_b32_e64 v79, 0, v79, s[34:35]
	v_cndmask_b32_e64 v81, 0, v81, s[38:39]
	v_cndmask_b32_e64 v1, 0, v1, s[42:43]
	v_cndmask_b32_e32 v2, 0, v2, vcc
.LBB0_392:
	v_cvt_pk_bf16_f32 v217, v2, v1
	v_add_f32_e32 v75, v82, v84
	v_add_f32_e32 v82, v85, v86
	ds_read_b64_tr_b16 v[84:85], v248 offset:12288
	ds_read_b64_tr_b16 v[86:87], v249 offset:13312
	ds_read_b64_tr_b16 v[100:101], v222 offset:12288
	ds_read_b64_tr_b16 v[102:103], v223 offset:12288
	ds_read_b64_tr_b16 v[116:117], v224 offset:12288
	ds_read_b64_tr_b16 v[118:119], v225 offset:12288
	ds_read_b64_tr_b16 v[218:219], v226 offset:12288
	ds_read_b64_tr_b16 v[220:221], v227 offset:12288
	v_add_f32_e32 v75, v82, v75
	v_cvt_pk_bf16_f32 v210, v68, v69
	v_cvt_pk_bf16_f32 v211, v70, v71
	v_cvt_pk_bf16_f32 v212, v72, v73
	v_cvt_pk_bf16_f32 v213, v74, v83
	v_add_f32_e32 v173, v173, v75
	v_cvt_pk_bf16_f32 v214, v76, v77
	v_cvt_pk_bf16_f32 v215, v78, v79
	v_cvt_pk_bf16_f32 v216, v80, v81
	s_waitcnt lgkmcnt(8)
	v_mfma_f32_32x32x16_bf16 v[36:51], v[228:231], v[210:213], v[36:51]
	s_cmp_eq_u32 s1, 0
	v_mfma_f32_32x32x16_bf16 v[52:67], v[232:235], v[210:213], v[52:67]
	v_mfma_f32_32x32x16_bf16 v[20:35], v[236:239], v[210:213], v[20:35]
	v_mfma_f32_32x32x16_bf16 v[4:19], v[240:243], v[210:213], v[4:19]
	s_waitcnt lgkmcnt(6)
	v_mfma_f32_32x32x16_bf16 v[36:51], v[84:87], v[214:217], v[36:51]
	s_waitcnt lgkmcnt(4)
	v_mfma_f32_32x32x16_bf16 v[52:67], v[100:103], v[214:217], v[52:67]
	s_waitcnt lgkmcnt(2)
	v_mfma_f32_32x32x16_bf16 v[20:35], v[116:119], v[214:217], v[20:35]
	s_waitcnt lgkmcnt(0)
	v_mfma_f32_32x32x16_bf16 v[4:19], v[218:221], v[214:217], v[4:19]
	s_cbranch_scc1 .LBB0_395
	v_cmp_lt_f32_e32 vcc, s5, v173
	s_cmp_eq_u64 vcc, 0
	s_cselect_b64 s[86:87], -1, 0
	s_and_saveexec_b64 s[90:91], s[8:9]
	s_cbranch_execz .LBB0_386
	s_branch .LBB0_396
